# v15 + GEMM1: leading half alignment barrier moved to just before the epilogue halo barrier
# baseline (speedup 1.0000x reference)
.Lg1_nopf:
	s_barrier
	v_mfma_f32_16x16x32_bf16 v[124:127], v[128:131], v[204:207], v[124:127]
	v_mfma_f32_16x16x32_bf16 v[120:123], v[136:139], v[204:207], v[120:123]
	v_mfma_f32_16x16x32_bf16 v[96:99], v[128:131], v[212:215], v[96:99]
	v_mfma_f32_16x16x32_bf16 v[88:91], v[136:139], v[212:215], v[88:91]
	v_mfma_f32_16x16x32_bf16 v[76:79], v[128:131], v[220:223], v[76:79]
	v_mfma_f32_16x16x32_bf16 v[72:75], v[136:139], v[220:223], v[72:75]
	v_mfma_f32_16x16x32_bf16 v[60:63], v[128:131], v[228:231], v[60:63]
	v_mfma_f32_16x16x32_bf16 v[108:111], v[136:139], v[228:231], v[108:111]
	v_mfma_f32_16x16x32_bf16 v[124:127], v[132:135], v[208:211], v[124:127]
	v_mfma_f32_16x16x32_bf16 v[120:123], v[158:161], v[208:211], v[120:123]
	v_mfma_f32_16x16x32_bf16 v[96:99], v[132:135], v[216:219], v[96:99]
	v_mfma_f32_16x16x32_bf16 v[88:91], v[158:161], v[216:219], v[88:91]
	v_mfma_f32_16x16x32_bf16 v[76:79], v[132:135], v[224:227], v[76:79]
	v_mfma_f32_16x16x32_bf16 v[72:75], v[158:161], v[224:227], v[72:75]
	v_mfma_f32_16x16x32_bf16 v[60:63], v[132:135], v[232:235], v[60:63]
	v_mfma_f32_16x16x32_bf16 v[108:111], v[158:161], v[232:235], v[108:111]
	v_mfma_f32_16x16x32_bf16 v[116:119], v[168:171], v[204:207], v[116:119]
	v_mfma_f32_16x16x32_bf16 v[112:115], v[196:199], v[204:207], v[112:115]
	v_mfma_f32_16x16x32_bf16 v[84:87], v[168:171], v[212:215], v[84:87]
	v_mfma_f32_16x16x32_bf16 v[80:83], v[196:199], v[212:215], v[80:83]
	v_mfma_f32_16x16x32_bf16 v[68:71], v[168:171], v[220:223], v[68:71]
	v_mfma_f32_16x16x32_bf16 v[64:67], v[196:199], v[220:223], v[64:67]
	v_mfma_f32_16x16x32_bf16 v[104:107], v[168:171], v[228:231], v[104:107]
	v_mfma_f32_16x16x32_bf16 v[56:59], v[196:199], v[228:231], v[56:59]
	v_mfma_f32_16x16x32_bf16 v[116:119], v[172:175], v[208:211], v[116:119]
	v_mfma_f32_16x16x32_bf16 v[112:115], v[200:203], v[208:211], v[112:115]
	v_mfma_f32_16x16x32_bf16 v[84:87], v[172:175], v[216:219], v[84:87]
	v_mfma_f32_16x16x32_bf16 v[80:83], v[200:203], v[216:219], v[80:83]
	v_mfma_f32_16x16x32_bf16 v[68:71], v[172:175], v[224:227], v[68:71]
	v_mfma_f32_16x16x32_bf16 v[64:67], v[200:203], v[224:227], v[64:67]
	v_mfma_f32_16x16x32_bf16 v[104:107], v[172:175], v[232:235], v[104:107]
	v_mfma_f32_16x16x32_bf16 v[56:59], v[200:203], v[232:235], v[56:59]
	s_barrier
	s_setprio 0
	s_add_i32 s87, s82, s23
	v_lshl_add_u64 v[162:163], s[66:67], 0, v[140:141]
	s_mov_b32 m0, s87
	ds_read_b128 v[204:207], v194 offset:16384
	ds_read_b128 v[208:211], v194 offset:17408
	ds_read_b128 v[212:215], v194 offset:18432
	ds_read_b128 v[216:219], v194 offset:19456
	ds_read_b128 v[220:223], v194 offset:20480
	ds_read_b128 v[224:227], v194 offset:21504
	ds_read_b128 v[228:231], v194 offset:22528
	ds_read_b128 v[232:235], v194 offset:23552
	global_load_lds_dwordx4 v[162:163], off
	s_add_i32 m0, s87, 0x2000
	s_add_u32 s88, s66, 0x40000
	v_lshl_add_u64 v[178:179], s[66:67], 0, v[142:143]
	s_addc_u32 s89, s67, 0
	s_add_i32 s87, s83, s23
	global_load_lds_dwordx4 v[178:179], off
	v_lshl_add_u64 v[184:185], s[88:89], 0, v[140:141]
	s_mov_b32 m0, s87
	v_lshl_add_u64 v[236:237], s[68:69], 0, v[142:143]
	global_load_lds_dwordx4 v[184:185], off
	v_lshl_add_u64 v[184:185], s[88:89], 0, v[142:143]
	s_add_i32 m0, s87, 0x2000
	s_nop 0
	global_load_lds_dwordx4 v[184:185], off
	v_lshl_add_u64 v[184:185], s[68:69], 0, v[140:141]
	s_mov_b32 m0, s70
	s_nop 0
	global_load_lds_dwordx4 v[184:185], off
	s_mov_b32 m0, s71
	s_nop 0
	global_load_lds_dwordx4 v[236:237], off
	s_waitcnt vmcnt(8)
	s_waitcnt lgkmcnt(0)
	s_setprio 1
	s_barrier
	v_mfma_f32_16x16x32_bf16 v[52:55], v[128:131], v[204:207], v[52:55]
	v_mfma_f32_16x16x32_bf16 v[48:51], v[136:139], v[204:207], v[48:51]
	v_mfma_f32_16x16x32_bf16 v[16:19], v[128:131], v[212:215], v[16:19]
	v_mfma_f32_16x16x32_bf16 v[8:11], v[136:139], v[212:215], v[8:11]
	v_mfma_f32_16x16x32_bf16 v[28:31], v[128:131], v[220:223], v[28:31]
	v_mfma_f32_16x16x32_bf16 v[24:27], v[136:139], v[220:223], v[24:27]
	v_mfma_f32_16x16x32_bf16 v[36:39], v[128:131], v[228:231], v[36:39]
	v_mfma_f32_16x16x32_bf16 v[100:103], v[136:139], v[228:231], v[100:103]
	v_mfma_f32_16x16x32_bf16 v[52:55], v[132:135], v[208:211], v[52:55]
	v_mfma_f32_16x16x32_bf16 v[48:51], v[158:161], v[208:211], v[48:51]
	v_mfma_f32_16x16x32_bf16 v[16:19], v[132:135], v[216:219], v[16:19]
	v_mfma_f32_16x16x32_bf16 v[8:11], v[158:161], v[216:219], v[8:11]
	v_mfma_f32_16x16x32_bf16 v[28:31], v[132:135], v[224:227], v[28:31]
	v_mfma_f32_16x16x32_bf16 v[24:27], v[158:161], v[224:227], v[24:27]
	v_mfma_f32_16x16x32_bf16 v[36:39], v[132:135], v[232:235], v[36:39]
	v_mfma_f32_16x16x32_bf16 v[100:103], v[158:161], v[232:235], v[100:103]
	v_mfma_f32_16x16x32_bf16 v[44:47], v[168:171], v[204:207], v[44:47]
	v_mfma_f32_16x16x32_bf16 v[40:43], v[196:199], v[204:207], v[40:43]
	v_mfma_f32_16x16x32_bf16 v[0:3], v[168:171], v[212:215], v[0:3]
	v_mfma_f32_16x16x32_bf16 v[4:7], v[196:199], v[212:215], v[4:7]
	v_mfma_f32_16x16x32_bf16 v[12:15], v[168:171], v[220:223], v[12:15]
	v_mfma_f32_16x16x32_bf16 v[20:23], v[196:199], v[220:223], v[20:23]
	v_mfma_f32_16x16x32_bf16 v[92:95], v[168:171], v[228:231], v[92:95]
	v_mfma_f32_16x16x32_bf16 v[32:35], v[196:199], v[228:231], v[32:35]
	v_mfma_f32_16x16x32_bf16 v[44:47], v[172:175], v[208:211], v[44:47]
	v_mfma_f32_16x16x32_bf16 v[40:43], v[200:203], v[208:211], v[40:43]
	v_mfma_f32_16x16x32_bf16 v[0:3], v[172:175], v[216:219], v[0:3]
	v_mfma_f32_16x16x32_bf16 v[4:7], v[200:203], v[216:219], v[4:7]
	v_mfma_f32_16x16x32_bf16 v[12:15], v[172:175], v[224:227], v[12:15]
	v_mfma_f32_16x16x32_bf16 v[20:23], v[200:203], v[224:227], v[20:23]
	v_mfma_f32_16x16x32_bf16 v[92:95], v[172:175], v[232:235], v[92:95]
	v_mfma_f32_16x16x32_bf16 v[32:35], v[200:203], v[232:235], v[32:35]
	s_barrier
	s_setprio 0
	s_add_i32 s87, 0, 0x18000
	s_add_i32 s88, 0, 0x1c000
	v_add_u32_e32 v158, s87, v167
	v_add_u32_e32 v164, s88, v167
	ds_read_b128 v[128:131], v158
	ds_read_b128 v[132:135], v158 offset:1024
	ds_read_b128 v[136:139], v158 offset:2048
	ds_read_b128 v[158:161], v158 offset:3072
	ds_read_b128 v[168:171], v164
	ds_read_b128 v[172:175], v164 offset:1024
	ds_read_b128 v[196:199], v164 offset:2048
	ds_read_b128 v[200:203], v164 offset:3072
	s_add_u32 s68, s68, 0x40000
	s_addc_u32 s69, s69, 0
	s_mov_b32 m0, s72
	v_lshl_add_u64 v[238:239], s[68:69], 0, v[140:141]
	ds_read_b128 v[204:207], v194 offset:32768
	ds_read_b128 v[208:211], v194 offset:33792
	ds_read_b128 v[212:215], v194 offset:34816
	ds_read_b128 v[216:219], v194 offset:35840
	ds_read_b128 v[220:223], v194 offset:36864
	ds_read_b128 v[224:227], v194 offset:37888
	ds_read_b128 v[228:231], v194 offset:38912
	ds_read_b128 v[232:235], v194 offset:39936
	global_load_lds_dwordx4 v[238:239], off
	v_lshl_add_u64 v[238:239], s[68:69], 0, v[142:143]
	s_mov_b32 m0, s73
	s_nop 0
	global_load_lds_dwordx4 v[238:239], off
	s_waitcnt vmcnt(8)
	s_waitcnt lgkmcnt(0)
	s_setprio 1
	s_barrier
	v_mfma_f32_16x16x32_bf16 v[124:127], v[128:131], v[204:207], v[124:127]
	v_mfma_f32_16x16x32_bf16 v[120:123], v[136:139], v[204:207], v[120:123]
	v_mfma_f32_16x16x32_bf16 v[96:99], v[128:131], v[212:215], v[96:99]
	v_mfma_f32_16x16x32_bf16 v[88:91], v[136:139], v[212:215], v[88:91]
	v_mfma_f32_16x16x32_bf16 v[76:79], v[128:131], v[220:223], v[76:79]
	v_mfma_f32_16x16x32_bf16 v[72:75], v[136:139], v[220:223], v[72:75]
	v_mfma_f32_16x16x32_bf16 v[60:63], v[128:131], v[228:231], v[60:63]
	v_mfma_f32_16x16x32_bf16 v[108:111], v[136:139], v[228:231], v[108:111]
	v_mfma_f32_16x16x32_bf16 v[124:127], v[132:135], v[208:211], v[124:127]
	v_mfma_f32_16x16x32_bf16 v[120:123], v[158:161], v[208:211], v[120:123]
	v_mfma_f32_16x16x32_bf16 v[96:99], v[132:135], v[216:219], v[96:99]
	v_mfma_f32_16x16x32_bf16 v[88:91], v[158:161], v[216:219], v[88:91]
	v_mfma_f32_16x16x32_bf16 v[76:79], v[132:135], v[224:227], v[76:79]
	v_mfma_f32_16x16x32_bf16 v[72:75], v[158:161], v[224:227], v[72:75]
	v_mfma_f32_16x16x32_bf16 v[60:63], v[132:135], v[232:235], v[60:63]
	v_mfma_f32_16x16x32_bf16 v[108:111], v[158:161], v[232:235], v[108:111]
	v_mfma_f32_16x16x32_bf16 v[116:119], v[168:171], v[204:207], v[116:119]
	v_mfma_f32_16x16x32_bf16 v[112:115], v[196:199], v[204:207], v[112:115]
	v_mfma_f32_16x16x32_bf16 v[84:87], v[168:171], v[212:215], v[84:87]
	v_mfma_f32_16x16x32_bf16 v[80:83], v[196:199], v[212:215], v[80:83]
	v_mfma_f32_16x16x32_bf16 v[68:71], v[168:171], v[220:223], v[68:71]
	v_mfma_f32_16x16x32_bf16 v[64:67], v[196:199], v[220:223], v[64:67]
	v_mfma_f32_16x16x32_bf16 v[104:107], v[168:171], v[228:231], v[104:107]
	v_mfma_f32_16x16x32_bf16 v[56:59], v[196:199], v[228:231], v[56:59]
	v_mfma_f32_16x16x32_bf16 v[116:119], v[172:175], v[208:211], v[116:119]
	v_mfma_f32_16x16x32_bf16 v[112:115], v[200:203], v[208:211], v[112:115]
	v_mfma_f32_16x16x32_bf16 v[84:87], v[172:175], v[216:219], v[84:87]
	v_mfma_f32_16x16x32_bf16 v[80:83], v[200:203], v[216:219], v[80:83]
	v_mfma_f32_16x16x32_bf16 v[68:71], v[172:175], v[224:227], v[68:71]
	v_mfma_f32_16x16x32_bf16 v[64:67], v[200:203], v[224:227], v[64:67]
	v_mfma_f32_16x16x32_bf16 v[104:107], v[172:175], v[232:235], v[104:107]
	v_mfma_f32_16x16x32_bf16 v[56:59], v[200:203], v[232:235], v[56:59]
	s_barrier
	s_setprio 0
	s_add_i32 s68, s87, s23
	v_lshl_add_u64 v[162:163], v[162:163], 0, s[36:37]
	s_mov_b32 m0, s68
	ds_read_b128 v[204:207], v194 offset:49152
	ds_read_b128 v[208:211], v194 offset:50176
	ds_read_b128 v[212:215], v194 offset:51200
	ds_read_b128 v[216:219], v194 offset:52224
	ds_read_b128 v[220:223], v194 offset:53248
	ds_read_b128 v[224:227], v194 offset:54272
	ds_read_b128 v[228:231], v194 offset:55296
	ds_read_b128 v[232:235], v194 offset:56320
	global_load_lds_dwordx4 v[162:163], off
	s_add_i32 m0, s68, 0x2000
	s_add_u32 s66, s66, 0x40080
	v_lshl_add_u64 v[162:163], v[178:179], 0, s[36:37]
	s_addc_u32 s67, s67, 0
	s_add_i32 s68, s88, s23
	global_load_lds_dwordx4 v[162:163], off
	v_lshl_add_u64 v[162:163], s[66:67], 0, v[140:141]
	s_mov_b32 m0, s68
	s_nop 0
	global_load_lds_dwordx4 v[162:163], off
	v_lshl_add_u64 v[162:163], s[66:67], 0, v[142:143]
	s_add_i32 m0, s68, 0x2000
	s_nop 0
	global_load_lds_dwordx4 v[162:163], off
	v_lshl_add_u64 v[162:163], v[184:185], 0, s[36:37]
	s_mov_b32 m0, s80
	s_nop 0
	global_load_lds_dwordx4 v[162:163], off
	v_lshl_add_u64 v[162:163], v[236:237], 0, s[36:37]
	s_mov_b32 m0, s81
	s_nop 0
	global_load_lds_dwordx4 v[162:163], off
	s_waitcnt vmcnt(8)
	s_waitcnt lgkmcnt(0)
	s_setprio 1
	s_barrier
	v_mfma_f32_16x16x32_bf16 v[52:55], v[128:131], v[204:207], v[52:55]
	v_mfma_f32_16x16x32_bf16 v[48:51], v[136:139], v[204:207], v[48:51]
	v_mfma_f32_16x16x32_bf16 v[16:19], v[128:131], v[212:215], v[16:19]
	v_mfma_f32_16x16x32_bf16 v[8:11], v[136:139], v[212:215], v[8:11]
	v_mfma_f32_16x16x32_bf16 v[28:31], v[128:131], v[220:223], v[28:31]
	v_mfma_f32_16x16x32_bf16 v[24:27], v[136:139], v[220:223], v[24:27]
	v_mfma_f32_16x16x32_bf16 v[36:39], v[128:131], v[228:231], v[36:39]
	v_mfma_f32_16x16x32_bf16 v[100:103], v[136:139], v[228:231], v[100:103]
	v_mfma_f32_16x16x32_bf16 v[52:55], v[132:135], v[208:211], v[52:55]
	v_mfma_f32_16x16x32_bf16 v[48:51], v[158:161], v[208:211], v[48:51]
	v_mfma_f32_16x16x32_bf16 v[16:19], v[132:135], v[216:219], v[16:19]
	v_mfma_f32_16x16x32_bf16 v[8:11], v[158:161], v[216:219], v[8:11]
	v_mfma_f32_16x16x32_bf16 v[28:31], v[132:135], v[224:227], v[28:31]
	v_mfma_f32_16x16x32_bf16 v[24:27], v[158:161], v[224:227], v[24:27]
	v_mfma_f32_16x16x32_bf16 v[36:39], v[132:135], v[232:235], v[36:39]
	v_mfma_f32_16x16x32_bf16 v[100:103], v[158:161], v[232:235], v[100:103]
	v_mfma_f32_16x16x32_bf16 v[44:47], v[168:171], v[204:207], v[44:47]
	v_mfma_f32_16x16x32_bf16 v[40:43], v[196:199], v[204:207], v[40:43]
	v_mfma_f32_16x16x32_bf16 v[0:3], v[168:171], v[212:215], v[0:3]
	v_mfma_f32_16x16x32_bf16 v[4:7], v[196:199], v[212:215], v[4:7]
	v_mfma_f32_16x16x32_bf16 v[12:15], v[168:171], v[220:223], v[12:15]
	v_mfma_f32_16x16x32_bf16 v[20:23], v[196:199], v[220:223], v[20:23]
	v_mfma_f32_16x16x32_bf16 v[92:95], v[168:171], v[228:231], v[92:95]
	v_mfma_f32_16x16x32_bf16 v[32:35], v[196:199], v[228:231], v[32:35]
	v_mfma_f32_16x16x32_bf16 v[44:47], v[172:175], v[208:211], v[44:47]
	v_mfma_f32_16x16x32_bf16 v[40:43], v[200:203], v[208:211], v[40:43]
	v_mfma_f32_16x16x32_bf16 v[0:3], v[172:175], v[216:219], v[0:3]
	v_mfma_f32_16x16x32_bf16 v[4:7], v[200:203], v[216:219], v[4:7]
	v_mfma_f32_16x16x32_bf16 v[12:15], v[172:175], v[224:227], v[12:15]
	v_mfma_f32_16x16x32_bf16 v[20:23], v[200:203], v[224:227], v[20:23]
	v_mfma_f32_16x16x32_bf16 v[92:95], v[172:175], v[232:235], v[92:95]
	v_mfma_f32_16x16x32_bf16 v[32:35], v[200:203], v[232:235], v[32:35]
	s_barrier
	s_setprio 0
	s_add_i32 s86, s86, 2
	s_add_u32 s64, s64, 0x100
	s_addc_u32 s65, s65, 0
	s_add_u32 s84, s84, 0x100
	s_addc_u32 s85, s85, 0
	s_cmp_gt_u32 s86, 13
	s_cbranch_scc0 .LBB0_439
.LBB0_442:
	s_lshl_b32 s55, s52, 8
	v_add_u32_e32 v184, s55, v165
	v_mbcnt_lo_u32_b32 v128, -1, 0
	v_mbcnt_hi_u32_b32 v128, -1, v128
	v_ashrrev_i32_e32 v185, 31, v184
	v_lshl_add_u64 v[128:129], v[184:185], 2, s[20:21]
	v_add_u32_e32 v158, 0xb0, v184
	v_add_u32_e32 v170, 0x80, v184
	v_add_u32_e32 v162, 0x90, v184
	v_add_u32_e32 v160, 0xa0, v184
	v_ashrrev_i32_e32 v159, 31, v158
	v_ashrrev_i32_e32 v171, 31, v170
	v_ashrrev_i32_e32 v163, 31, v162
	v_ashrrev_i32_e32 v161, 31, v160
	v_lshl_add_u64 v[136:137], v[158:159], 2, s[20:21]
	v_lshl_add_u64 v[130:131], v[170:171], 2, s[20:21]
	v_lshl_add_u64 v[132:133], v[162:163], 2, s[20:21]
	v_lshl_add_u64 v[134:135], v[160:161], 2, s[20:21]
	s_waitcnt vmcnt(14)
	v_mov_b32_e32 v178, v245
	v_mov_b32_e32 v168, v250
	v_mov_b32_e32 v186, v242
	v_mov_b32_e32 v182, v243
	v_mov_b32_e32 v180, v244
	v_mov_b32_e32 v176, v246
	v_mov_b32_e32 v164, v248
	v_mov_b32_e32 v166, v249
	v_pk_mul_f32 v[108:109], v[108:109], v[178:179] op_sel_hi:[1,0]
	v_pk_mul_f32 v[110:111], v[110:111], v[178:179] op_sel_hi:[1,0]
	v_pk_mul_f32 v[104:105], v[104:105], v[178:179] op_sel_hi:[1,0]
	v_pk_mul_f32 v[106:107], v[106:107], v[178:179] op_sel_hi:[1,0]
	v_pk_mul_f32 v[128:129], v[108:109], v[104:105]
	v_pk_mul_f32 v[130:131], v[110:111], v[106:107]
	v_pk_mul_f32 v[100:101], v[100:101], v[168:169] op_sel_hi:[1,0]
	v_pk_mul_f32 v[102:103], v[102:103], v[168:169] op_sel_hi:[1,0]
	v_pk_mul_f32 v[92:93], v[92:93], v[168:169] op_sel_hi:[1,0]
	v_pk_mul_f32 v[94:95], v[94:95], v[168:169] op_sel_hi:[1,0]
	v_pk_mul_f32 v[92:93], v[100:101], v[92:93]
	v_pk_mul_f32 v[94:95], v[102:103], v[94:95]
	s_and_saveexec_b64 s[64:65], s[4:5]
	s_cbranch_execz .LBB0_444
	ds_write_b128 v195, v[128:131]
	ds_write_b128 v195, v[92:95] offset:1024

.LBB0_446:
	s_or_b64 exec, exec, s[62:63]
	v_lshlrev_b64 v[174:175], 2, v[172:173]
	s_waitcnt lgkmcnt(0)
	s_and_b64 vcc, exec, s[38:39]
	s_cbranch_vccz .Lg1_align
	s_barrier
.Lg1_align:
	s_barrier
	v_add_u32_e32 v100, 0x22000, v174
	ds_read_b128 v[108:111], v100
	ds_read_b128 v[104:107], v100 offset:4096
	ds_read_b128 v[100:103], v100 offset:8192
	s_andn2_b64 vcc, exec, s[42:43]
	s_cbranch_vccnz .LBB0_448
	ds_read_b128 v[136:139], v189
	ds_read_b128 v[132:135], v188
	s_branch .LBB0_449
